# phase 7 (out projection + residual) as B-shared dual-tile mainloop with W double-buffered in LDS + own f32 residual epilogue for both tiles
# speedup vs baseline: 1.1155x; 1.0016x over previous
.LBB0_538:
	v_and_b32_e32 v236, 15, v168
	v_lshrrev_b32_e32 v237, 1, v236
	v_bfe_u32 v238, v168, 4, 2
	v_xor_b32_e32 v237, v237, v238
	v_lshlrev_b32_e32 v237, 4, v237
	v_lshl_or_b32 v236, v236, 7, v237
	v_xor_b32_e32 v237, 64, v236
	v_add_u32_e32 v236, 16, v236
	v_add_u32_e32 v237, 16, v237
	v_bfe_u32 v238, v168, 7, 1
	v_lshl_add_u32 v240, v238, 13, v237
	v_lshl_add_u32 v238, v238, 13, v236
	v_bfe_u32 v239, v168, 6, 1
	v_lshl_add_u32 v241, v239, 13, v237
	v_lshl_add_u32 v239, v239, 13, v236
	v_lshrrev_b32_e32 v236, 3, v168
	v_lshrrev_b32_e32 v237, 4, v168
	v_xor_b32_e32 v237, v237, v168
	v_and_b32_e32 v237, 7, v237
	v_lshlrev_b32_e32 v237, 4, v237
	v_lshl_or_b32 v232, v236, 11, v237
	v_add_u32_e32 v233, 0x10000, v232
	v_add_u32_e32 v234, 0x20000, v232
	v_add_u32_e32 v235, 0x30000, v232
	s_load_dwordx2 s[90:91], s[0:1], 0xd8
	s_load_dwordx2 s[92:93], s[0:1], 0xc0
	v_lshrrev_b32_e32 v237, 6, v168
	s_nop 1
	v_readfirstlane_b32 s97, v237
	s_nop 3
	s_lshl_b32 s96, s97, 10
	s_add_u32 s96, s96, 16
	s_add_u32 s94, s61, s60
	s_cmp_lt_i32 s94, s62
	s_cselect_b32 s95, 1, 0
	s_cmp_lg_u64 s[12:13], 0
	s_cselect_b32 s95, 0, s95
	s_cmp_ge_u32 s94, 0x40
	s_cselect_b32 s97, 1, 0
	s_mul_i32 s100, s97, 0x40
	s_sub_u32 s100, s94, s100
	s_lshr_b32 s101, s100, 3
	s_and_b32 s100, s100, 7
	s_lshl_b32 s97, s97, 3
	s_add_u32 s100, s100, s97
	s_add_u32 s100, s100, s3
	s_cmp_lg_u32 s101, s48
	s_cselect_b32 s95, 0, s95
	s_cmp_eq_u32 s95, 1
	s_cselect_b32 s101, s100, s50
	s_mov_b32 s97, s101
	s_waitcnt lgkmcnt(0)
	s_lshl_b32 s94, s48, 18
	s_add_u32 s98, s92, s94
	s_addc_u32 s99, s93, 0
	s_lshl_b32 s101, s101, 18
	s_add_u32 s92, s90, s101
	s_addc_u32 s93, s91, 0
	s_lshl_b32 s94, s50, 18
	s_add_u32 s90, s90, s94
	s_addc_u32 s91, s91, 0
	s_mov_b64 s[100:101], s[90:91]
	s_mov_b64 s[90:91], s[98:99]
	s_mov_b64 s[98:99], s[92:93]
	s_mov_b64 s[92:93], s[100:101]
	s_waitcnt vmcnt(0)
	s_barrier
	s_add_u32 m0, s96, 0x0
	s_nop 0
	global_load_lds_dwordx4 v232, s[90:91]
	s_add_u32 m0, s96, 0x1000
	s_nop 0
	global_load_lds_dwordx4 v233, s[90:91]
	s_add_u32 m0, s96, 0x2000
	s_nop 0
	global_load_lds_dwordx4 v234, s[90:91]
	s_add_u32 m0, s96, 0x3000
	s_nop 0
	global_load_lds_dwordx4 v235, s[90:91]
	s_add_u32 m0, s96, 0x8000
	s_nop 0
	global_load_lds_dwordx4 v232, s[92:93]
	s_add_u32 m0, s96, 0x9000
	s_nop 0
	global_load_lds_dwordx4 v233, s[92:93]
	s_add_u32 m0, s96, 0xa000
	s_nop 0
	global_load_lds_dwordx4 v234, s[92:93]
	s_add_u32 m0, s96, 0xb000
	s_nop 0
	global_load_lds_dwordx4 v235, s[92:93]
	s_add_u32 m0, s96, 0xc000
	s_nop 0
	global_load_lds_dwordx4 v232, s[98:99]
	s_add_u32 m0, s96, 0xd000
	s_nop 0
	global_load_lds_dwordx4 v233, s[98:99]
	s_add_u32 m0, s96, 0xe000
	s_nop 0
	global_load_lds_dwordx4 v234, s[98:99]
	s_add_u32 m0, s96, 0xf000
	s_nop 0
	global_load_lds_dwordx4 v235, s[98:99]
	s_add_u32 s90, s90, 0x80
	s_addc_u32 s91, s91, 0
	s_add_u32 s92, s92, 0x80
	s_addc_u32 s93, s93, 0
	s_add_u32 s98, s98, 0x80
	s_addc_u32 s99, s99, 0
	s_and_b64 vcc, exec, s[6:7]
	s_cbranch_vccnz .Lgp7_nosleep
	s_sleep 8
.Lgp7_nosleep:
	v_mov_b32_e32 v0, 0
	v_mov_b32_e32 v1, v0
	v_mov_b32_e32 v2, v0
	v_mov_b32_e32 v3, v0
	v_mov_b32_e32 v4, v0
	v_mov_b32_e32 v5, v0
	v_mov_b32_e32 v6, v0
	v_mov_b32_e32 v7, v0
	v_mov_b32_e32 v8, v0
	v_mov_b32_e32 v9, v0
	v_mov_b32_e32 v10, v0
	v_mov_b32_e32 v11, v0
	v_mov_b32_e32 v12, v0
	v_mov_b32_e32 v13, v0
	v_mov_b32_e32 v14, v0
	v_mov_b32_e32 v15, v0
	v_mov_b32_e32 v16, v0
	v_mov_b32_e32 v17, v0
	v_mov_b32_e32 v18, v0
	v_mov_b32_e32 v19, v0
	v_mov_b32_e32 v20, v0
	v_mov_b32_e32 v21, v0
	v_mov_b32_e32 v22, v0
	v_mov_b32_e32 v23, v0
	v_mov_b32_e32 v24, v0
	v_mov_b32_e32 v25, v0
	v_mov_b32_e32 v26, v0
	v_mov_b32_e32 v27, v0
	v_mov_b32_e32 v28, v0
	v_mov_b32_e32 v29, v0
	v_mov_b32_e32 v30, v0
	v_mov_b32_e32 v31, v0
	v_mov_b32_e32 v32, v0
	v_mov_b32_e32 v33, v0
	v_mov_b32_e32 v34, v0
	v_mov_b32_e32 v35, v0
	v_mov_b32_e32 v36, v0
	v_mov_b32_e32 v37, v0
	v_mov_b32_e32 v38, v0
	v_mov_b32_e32 v39, v0
	v_mov_b32_e32 v40, v0
	v_mov_b32_e32 v41, v0
	v_mov_b32_e32 v42, v0
	v_mov_b32_e32 v43, v0
	v_mov_b32_e32 v44, v0
	v_mov_b32_e32 v45, v0
	v_mov_b32_e32 v46, v0
	v_mov_b32_e32 v47, v0
	v_mov_b32_e32 v48, v0
	v_mov_b32_e32 v49, v0
	v_mov_b32_e32 v50, v0
	v_mov_b32_e32 v51, v0
	v_mov_b32_e32 v52, v0
	v_mov_b32_e32 v53, v0
	v_mov_b32_e32 v54, v0
	v_mov_b32_e32 v55, v0
	v_mov_b32_e32 v56, v0
	v_mov_b32_e32 v57, v0
	v_mov_b32_e32 v58, v0
	v_mov_b32_e32 v59, v0
	v_mov_b32_e32 v60, v0
	v_mov_b32_e32 v61, v0
	v_mov_b32_e32 v62, v0
	v_mov_b32_e32 v63, v0
	v_mov_b32_e32 v64, v0
	v_mov_b32_e32 v65, v0
	v_mov_b32_e32 v66, v0
	v_mov_b32_e32 v67, v0
	v_mov_b32_e32 v68, v0
	v_mov_b32_e32 v69, v0
	v_mov_b32_e32 v70, v0
	v_mov_b32_e32 v71, v0
	v_mov_b32_e32 v72, v0
	v_mov_b32_e32 v73, v0
	v_mov_b32_e32 v74, v0
	v_mov_b32_e32 v75, v0
	v_mov_b32_e32 v76, v0
	v_mov_b32_e32 v77, v0
	v_mov_b32_e32 v78, v0
	v_mov_b32_e32 v79, v0
	v_mov_b32_e32 v80, v0
	v_mov_b32_e32 v81, v0
	v_mov_b32_e32 v82, v0
	v_mov_b32_e32 v83, v0
	v_mov_b32_e32 v84, v0
	v_mov_b32_e32 v85, v0
	v_mov_b32_e32 v86, v0
	v_mov_b32_e32 v87, v0
	v_mov_b32_e32 v88, v0
	v_mov_b32_e32 v89, v0
	v_mov_b32_e32 v90, v0
	v_mov_b32_e32 v91, v0
	v_mov_b32_e32 v92, v0
	v_mov_b32_e32 v93, v0
	v_mov_b32_e32 v94, v0
	v_mov_b32_e32 v95, v0
	v_mov_b32_e32 v96, v0
	v_mov_b32_e32 v97, v0
	v_mov_b32_e32 v98, v0
	v_mov_b32_e32 v99, v0
	v_mov_b32_e32 v100, v0
	v_mov_b32_e32 v101, v0
	v_mov_b32_e32 v102, v0
	v_mov_b32_e32 v103, v0
	v_mov_b32_e32 v104, v0
	v_mov_b32_e32 v105, v0
	v_mov_b32_e32 v106, v0
	v_mov_b32_e32 v107, v0
	v_mov_b32_e32 v108, v0
	v_mov_b32_e32 v109, v0
	v_mov_b32_e32 v110, v0
	v_mov_b32_e32 v111, v0
	v_mov_b32_e32 v112, v0
	v_mov_b32_e32 v113, v0
	v_mov_b32_e32 v114, v0
	v_mov_b32_e32 v115, v0
	v_mov_b32_e32 v116, v0
	v_mov_b32_e32 v117, v0
	v_mov_b32_e32 v118, v0
	v_mov_b32_e32 v119, v0
	v_mov_b32_e32 v120, v0
	v_mov_b32_e32 v121, v0
	v_mov_b32_e32 v122, v0
	v_mov_b32_e32 v123, v0
	v_mov_b32_e32 v124, v0
	v_mov_b32_e32 v125, v0
	v_mov_b32_e32 v126, v0
	v_mov_b32_e32 v127, v0
	s_mov_b32 s94, 0

.Lgp7_last:
	v_mfma_f32_16x16x32_bf16 v[0:3], v[128:131], v[164:167], v[0:3]
	v_mfma_f32_16x16x32_bf16 v[64:67], v[128:131], v[200:203], v[64:67]
	v_mfma_f32_16x16x32_bf16 v[4:7], v[132:135], v[164:167], v[4:7]
	v_mfma_f32_16x16x32_bf16 v[68:71], v[132:135], v[200:203], v[68:71]
	v_mfma_f32_16x16x32_bf16 v[8:11], v[136:139], v[164:167], v[8:11]
	v_mfma_f32_16x16x32_bf16 v[72:75], v[136:139], v[200:203], v[72:75]
	v_mfma_f32_16x16x32_bf16 v[12:15], v[140:143], v[164:167], v[12:15]
	v_mfma_f32_16x16x32_bf16 v[76:79], v[140:143], v[200:203], v[76:79]
	v_mfma_f32_16x16x32_bf16 v[16:19], v[128:131], v[172:175], v[16:19]
	v_mfma_f32_16x16x32_bf16 v[80:83], v[128:131], v[204:207], v[80:83]
	v_mfma_f32_16x16x32_bf16 v[20:23], v[132:135], v[172:175], v[20:23]
	v_mfma_f32_16x16x32_bf16 v[84:87], v[132:135], v[204:207], v[84:87]
	v_mfma_f32_16x16x32_bf16 v[24:27], v[136:139], v[172:175], v[24:27]
	v_mfma_f32_16x16x32_bf16 v[88:91], v[136:139], v[204:207], v[88:91]
	v_mfma_f32_16x16x32_bf16 v[28:31], v[140:143], v[172:175], v[28:31]
	v_mfma_f32_16x16x32_bf16 v[92:95], v[140:143], v[204:207], v[92:95]
	v_mfma_f32_16x16x32_bf16 v[32:35], v[128:131], v[176:179], v[32:35]
	v_mfma_f32_16x16x32_bf16 v[96:99], v[128:131], v[208:211], v[96:99]
	v_mfma_f32_16x16x32_bf16 v[36:39], v[132:135], v[176:179], v[36:39]
	v_mfma_f32_16x16x32_bf16 v[100:103], v[132:135], v[208:211], v[100:103]
	v_mfma_f32_16x16x32_bf16 v[40:43], v[136:139], v[176:179], v[40:43]
	v_mfma_f32_16x16x32_bf16 v[104:107], v[136:139], v[208:211], v[104:107]
	v_mfma_f32_16x16x32_bf16 v[44:47], v[140:143], v[176:179], v[44:47]
	v_mfma_f32_16x16x32_bf16 v[108:111], v[140:143], v[208:211], v[108:111]
	v_mfma_f32_16x16x32_bf16 v[48:51], v[128:131], v[180:183], v[48:51]
	v_mfma_f32_16x16x32_bf16 v[112:115], v[128:131], v[212:215], v[112:115]
	v_mfma_f32_16x16x32_bf16 v[52:55], v[132:135], v[180:183], v[52:55]
	v_mfma_f32_16x16x32_bf16 v[116:119], v[132:135], v[212:215], v[116:119]
	v_mfma_f32_16x16x32_bf16 v[56:59], v[136:139], v[180:183], v[56:59]
	v_mfma_f32_16x16x32_bf16 v[120:123], v[136:139], v[212:215], v[120:123]
	v_mfma_f32_16x16x32_bf16 v[60:63], v[140:143], v[180:183], v[60:63]
	v_mfma_f32_16x16x32_bf16 v[124:127], v[140:143], v[212:215], v[124:127]
	s_waitcnt lgkmcnt(0)
	v_mfma_f32_16x16x32_bf16 v[0:3], v[148:151], v[184:187], v[0:3]
	v_mfma_f32_16x16x32_bf16 v[64:67], v[148:151], v[216:219], v[64:67]
	v_mfma_f32_16x16x32_bf16 v[4:7], v[152:155], v[184:187], v[4:7]
	v_mfma_f32_16x16x32_bf16 v[68:71], v[152:155], v[216:219], v[68:71]
	v_mfma_f32_16x16x32_bf16 v[8:11], v[156:159], v[184:187], v[8:11]
	v_mfma_f32_16x16x32_bf16 v[72:75], v[156:159], v[216:219], v[72:75]
	v_mfma_f32_16x16x32_bf16 v[12:15], v[160:163], v[184:187], v[12:15]
	v_mfma_f32_16x16x32_bf16 v[76:79], v[160:163], v[216:219], v[76:79]
	v_mfma_f32_16x16x32_bf16 v[16:19], v[148:151], v[188:191], v[16:19]
	v_mfma_f32_16x16x32_bf16 v[80:83], v[148:151], v[220:223], v[80:83]
	v_mfma_f32_16x16x32_bf16 v[20:23], v[152:155], v[188:191], v[20:23]
	v_mfma_f32_16x16x32_bf16 v[84:87], v[152:155], v[220:223], v[84:87]
	v_mfma_f32_16x16x32_bf16 v[24:27], v[156:159], v[188:191], v[24:27]
	v_mfma_f32_16x16x32_bf16 v[88:91], v[156:159], v[220:223], v[88:91]
	v_mfma_f32_16x16x32_bf16 v[28:31], v[160:163], v[188:191], v[28:31]
	v_mfma_f32_16x16x32_bf16 v[92:95], v[160:163], v[220:223], v[92:95]
	v_mfma_f32_16x16x32_bf16 v[32:35], v[148:151], v[192:195], v[32:35]
	v_mfma_f32_16x16x32_bf16 v[96:99], v[148:151], v[224:227], v[96:99]
	v_mfma_f32_16x16x32_bf16 v[36:39], v[152:155], v[192:195], v[36:39]
	v_mfma_f32_16x16x32_bf16 v[100:103], v[152:155], v[224:227], v[100:103]
	v_mfma_f32_16x16x32_bf16 v[40:43], v[156:159], v[192:195], v[40:43]
	v_mfma_f32_16x16x32_bf16 v[104:107], v[156:159], v[224:227], v[104:107]
	v_mfma_f32_16x16x32_bf16 v[44:47], v[160:163], v[192:195], v[44:47]
	v_mfma_f32_16x16x32_bf16 v[108:111], v[160:163], v[224:227], v[108:111]
	v_mfma_f32_16x16x32_bf16 v[48:51], v[148:151], v[196:199], v[48:51]
	v_mfma_f32_16x16x32_bf16 v[112:115], v[148:151], v[228:231], v[112:115]
	v_mfma_f32_16x16x32_bf16 v[52:55], v[152:155], v[196:199], v[52:55]
	v_mfma_f32_16x16x32_bf16 v[116:119], v[152:155], v[228:231], v[116:119]
	v_mfma_f32_16x16x32_bf16 v[56:59], v[156:159], v[196:199], v[56:59]
	v_mfma_f32_16x16x32_bf16 v[120:123], v[156:159], v[228:231], v[120:123]
	v_mfma_f32_16x16x32_bf16 v[60:63], v[160:163], v[196:199], v[60:63]
	v_mfma_f32_16x16x32_bf16 v[124:127], v[160:163], v[228:231], v[124:127]
	s_nop 7
	s_nop 3
	v_lshrrev_b32_e32 v246, 1, v168
	v_and_b32_e32 v246, 0x1c0, v246
	v_and_b32_e32 v247, 15, v168
	v_or_b32_e32 v246, v246, v247
	v_lshl_add_u32 v246, s50, 7, v246
	v_lshrrev_b32_e32 v247, 2, v168
	v_and_b32_e32 v247, 12, v247
	v_and_or_b32 v247, v168, 64, v247
	v_lshl_add_u32 v247, s48, 7, v247
	v_lshlrev_b32_e32 v247, 2, v247
	v_lshl_add_u32 v242, v246, 12, v247
	v_add_u32_e32 v243, 0x10000, v242
	v_add_u32_e32 v244, 0x20000, v242
	v_add_u32_e32 v245, 0x30000, v242
	global_load_dwordx4 v[128:131], v242, s[14:15]
	global_load_dwordx4 v[132:135], v242, s[14:15] offset:64
	global_load_dwordx4 v[136:139], v242, s[14:15] offset:128
	global_load_dwordx4 v[140:143], v242, s[14:15] offset:192
	global_load_dwordx4 v[148:151], v243, s[14:15]
	global_load_dwordx4 v[152:155], v243, s[14:15] offset:64
	global_load_dwordx4 v[156:159], v243, s[14:15] offset:128
	global_load_dwordx4 v[160:163], v243, s[14:15] offset:192
	global_load_dwordx4 v[164:167], v244, s[14:15]
	global_load_dwordx4 v[172:175], v244, s[14:15] offset:64
	global_load_dwordx4 v[176:179], v244, s[14:15] offset:128
	global_load_dwordx4 v[180:183], v244, s[14:15] offset:192
	global_load_dwordx4 v[184:187], v245, s[14:15]
	global_load_dwordx4 v[188:191], v245, s[14:15] offset:64
	global_load_dwordx4 v[192:195], v245, s[14:15] offset:128
	global_load_dwordx4 v[196:199], v245, s[14:15] offset:192
	s_waitcnt vmcnt(15)
	v_pk_add_f32 v[0:1], v[0:1], v[128:129]
	v_pk_add_f32 v[2:3], v[2:3], v[130:131]
	global_store_dwordx4 v242, v[0:3], s[10:11]
	s_waitcnt vmcnt(15)
	v_pk_add_f32 v[4:5], v[4:5], v[132:133]
	v_pk_add_f32 v[6:7], v[6:7], v[134:135]
	global_store_dwordx4 v242, v[4:7], s[10:11] offset:64
	s_waitcnt vmcnt(15)
	v_pk_add_f32 v[8:9], v[8:9], v[136:137]
	v_pk_add_f32 v[10:11], v[10:11], v[138:139]
	global_store_dwordx4 v242, v[8:11], s[10:11] offset:128
	s_waitcnt vmcnt(15)
	v_pk_add_f32 v[12:13], v[12:13], v[140:141]
	v_pk_add_f32 v[14:15], v[14:15], v[142:143]
	global_store_dwordx4 v242, v[12:15], s[10:11] offset:192
	s_waitcnt vmcnt(15)
	v_pk_add_f32 v[16:17], v[16:17], v[148:149]
	v_pk_add_f32 v[18:19], v[18:19], v[150:151]
	global_store_dwordx4 v243, v[16:19], s[10:11]
	s_waitcnt vmcnt(15)
	v_pk_add_f32 v[20:21], v[20:21], v[152:153]
	v_pk_add_f32 v[22:23], v[22:23], v[154:155]
	global_store_dwordx4 v243, v[20:23], s[10:11] offset:64
	s_waitcnt vmcnt(15)
	v_pk_add_f32 v[24:25], v[24:25], v[156:157]
	v_pk_add_f32 v[26:27], v[26:27], v[158:159]
	global_store_dwordx4 v243, v[24:27], s[10:11] offset:128
	s_waitcnt vmcnt(15)
	v_pk_add_f32 v[28:29], v[28:29], v[160:161]
	v_pk_add_f32 v[30:31], v[30:31], v[162:163]
	global_store_dwordx4 v243, v[28:31], s[10:11] offset:192
	s_waitcnt vmcnt(15)
	v_pk_add_f32 v[32:33], v[32:33], v[164:165]
	v_pk_add_f32 v[34:35], v[34:35], v[166:167]
	global_store_dwordx4 v244, v[32:35], s[10:11]
	s_waitcnt vmcnt(15)
	v_pk_add_f32 v[36:37], v[36:37], v[172:173]
	v_pk_add_f32 v[38:39], v[38:39], v[174:175]
	global_store_dwordx4 v244, v[36:39], s[10:11] offset:64
	s_waitcnt vmcnt(15)
	v_pk_add_f32 v[40:41], v[40:41], v[176:177]
	v_pk_add_f32 v[42:43], v[42:43], v[178:179]
	global_store_dwordx4 v244, v[40:43], s[10:11] offset:128
	s_waitcnt vmcnt(15)
	v_pk_add_f32 v[44:45], v[44:45], v[180:181]
	v_pk_add_f32 v[46:47], v[46:47], v[182:183]
	global_store_dwordx4 v244, v[44:47], s[10:11] offset:192
	s_waitcnt vmcnt(15)
	v_pk_add_f32 v[48:49], v[48:49], v[184:185]
	v_pk_add_f32 v[50:51], v[50:51], v[186:187]
	global_store_dwordx4 v245, v[48:51], s[10:11]
	s_waitcnt vmcnt(15)
	v_pk_add_f32 v[52:53], v[52:53], v[188:189]
	v_pk_add_f32 v[54:55], v[54:55], v[190:191]
	global_store_dwordx4 v245, v[52:55], s[10:11] offset:64
	s_waitcnt vmcnt(15)
	v_pk_add_f32 v[56:57], v[56:57], v[192:193]
	v_pk_add_f32 v[58:59], v[58:59], v[194:195]
	global_store_dwordx4 v245, v[56:59], s[10:11] offset:128
	s_waitcnt vmcnt(15)
	v_pk_add_f32 v[60:61], v[60:61], v[196:197]
	v_pk_add_f32 v[62:63], v[62:63], v[198:199]
	global_store_dwordx4 v245, v[60:63], s[10:11] offset:192
	s_add_i32 s61, s61, s60
	s_cmp_eq_u32 s95, 1
	s_cbranch_scc0 .Lgp7_single
	v_lshrrev_b32_e32 v246, 1, v168
	v_and_b32_e32 v246, 0x1c0, v246
	v_and_b32_e32 v247, 15, v168
	v_or_b32_e32 v246, v246, v247
	v_lshl_add_u32 v246, s97, 7, v246
	v_lshrrev_b32_e32 v247, 2, v168
	v_and_b32_e32 v247, 12, v247
	v_and_or_b32 v247, v168, 64, v247
	v_lshl_add_u32 v247, s48, 7, v247
	v_lshlrev_b32_e32 v247, 2, v247
	v_lshl_add_u32 v242, v246, 12, v247
	v_add_u32_e32 v243, 0x10000, v242
	v_add_u32_e32 v244, 0x20000, v242
	v_add_u32_e32 v245, 0x30000, v242
	global_load_dwordx4 v[128:131], v242, s[14:15]
	global_load_dwordx4 v[132:135], v242, s[14:15] offset:64
	global_load_dwordx4 v[136:139], v242, s[14:15] offset:128
	global_load_dwordx4 v[140:143], v242, s[14:15] offset:192
	global_load_dwordx4 v[148:151], v243, s[14:15]
	global_load_dwordx4 v[152:155], v243, s[14:15] offset:64
	global_load_dwordx4 v[156:159], v243, s[14:15] offset:128
	global_load_dwordx4 v[160:163], v243, s[14:15] offset:192
	global_load_dwordx4 v[164:167], v244, s[14:15]
	global_load_dwordx4 v[172:175], v244, s[14:15] offset:64
	global_load_dwordx4 v[176:179], v244, s[14:15] offset:128
	global_load_dwordx4 v[180:183], v244, s[14:15] offset:192
	global_load_dwordx4 v[184:187], v245, s[14:15]
	global_load_dwordx4 v[188:191], v245, s[14:15] offset:64
	global_load_dwordx4 v[192:195], v245, s[14:15] offset:128
	global_load_dwordx4 v[196:199], v245, s[14:15] offset:192
	s_waitcnt vmcnt(15)
	v_pk_add_f32 v[64:65], v[64:65], v[128:129]
	v_pk_add_f32 v[66:67], v[66:67], v[130:131]
	global_store_dwordx4 v242, v[64:67], s[10:11]
	s_waitcnt vmcnt(15)
	v_pk_add_f32 v[68:69], v[68:69], v[132:133]
	v_pk_add_f32 v[70:71], v[70:71], v[134:135]
	global_store_dwordx4 v242, v[68:71], s[10:11] offset:64
	s_waitcnt vmcnt(15)
	v_pk_add_f32 v[72:73], v[72:73], v[136:137]
	v_pk_add_f32 v[74:75], v[74:75], v[138:139]
	global_store_dwordx4 v242, v[72:75], s[10:11] offset:128
	s_waitcnt vmcnt(15)
	v_pk_add_f32 v[76:77], v[76:77], v[140:141]
	v_pk_add_f32 v[78:79], v[78:79], v[142:143]
	global_store_dwordx4 v242, v[76:79], s[10:11] offset:192
	s_waitcnt vmcnt(15)
	v_pk_add_f32 v[80:81], v[80:81], v[148:149]
	v_pk_add_f32 v[82:83], v[82:83], v[150:151]
	global_store_dwordx4 v243, v[80:83], s[10:11]
	s_waitcnt vmcnt(15)
	v_pk_add_f32 v[84:85], v[84:85], v[152:153]
	v_pk_add_f32 v[86:87], v[86:87], v[154:155]
	global_store_dwordx4 v243, v[84:87], s[10:11] offset:64
	s_waitcnt vmcnt(15)
	v_pk_add_f32 v[88:89], v[88:89], v[156:157]
	v_pk_add_f32 v[90:91], v[90:91], v[158:159]
	global_store_dwordx4 v243, v[88:91], s[10:11] offset:128
	s_waitcnt vmcnt(15)
	v_pk_add_f32 v[92:93], v[92:93], v[160:161]
	v_pk_add_f32 v[94:95], v[94:95], v[162:163]
	global_store_dwordx4 v243, v[92:95], s[10:11] offset:192
	s_waitcnt vmcnt(15)
	v_pk_add_f32 v[96:97], v[96:97], v[164:165]
	v_pk_add_f32 v[98:99], v[98:99], v[166:167]
	global_store_dwordx4 v244, v[96:99], s[10:11]
	s_waitcnt vmcnt(15)
	v_pk_add_f32 v[100:101], v[100:101], v[172:173]
	v_pk_add_f32 v[102:103], v[102:103], v[174:175]
	global_store_dwordx4 v244, v[100:103], s[10:11] offset:64
	s_waitcnt vmcnt(15)
	v_pk_add_f32 v[104:105], v[104:105], v[176:177]
	v_pk_add_f32 v[106:107], v[106:107], v[178:179]
	global_store_dwordx4 v244, v[104:107], s[10:11] offset:128
	s_waitcnt vmcnt(15)
	v_pk_add_f32 v[108:109], v[108:109], v[180:181]
	v_pk_add_f32 v[110:111], v[110:111], v[182:183]
	global_store_dwordx4 v244, v[108:111], s[10:11] offset:192
	s_waitcnt vmcnt(15)
	v_pk_add_f32 v[112:113], v[112:113], v[184:185]
	v_pk_add_f32 v[114:115], v[114:115], v[186:187]
	global_store_dwordx4 v245, v[112:115], s[10:11]
	s_waitcnt vmcnt(15)
	v_pk_add_f32 v[116:117], v[116:117], v[188:189]
	v_pk_add_f32 v[118:119], v[118:119], v[190:191]
	global_store_dwordx4 v245, v[116:119], s[10:11] offset:64
	s_waitcnt vmcnt(15)
	v_pk_add_f32 v[120:121], v[120:121], v[192:193]
	v_pk_add_f32 v[122:123], v[122:123], v[194:195]
	global_store_dwordx4 v245, v[120:123], s[10:11] offset:128
	s_waitcnt vmcnt(15)
	v_pk_add_f32 v[124:125], v[124:125], v[196:197]
	v_pk_add_f32 v[126:127], v[126:127], v[198:199]
	global_store_dwordx4 v245, v[124:127], s[10:11] offset:192
	s_add_i32 s61, s61, s60
.Lgp7_single:
	s_mov_b32 s95, 0
	s_cmp_lt_i32 s61, s62
	s_cbranch_scc1 .LBB0_534
